# v36 + tail_glu/tail_mix: vmcnt(0) before their closing barrier dropped (outputs are consumed only after the phase-end wait and grid barrier)
# speedup vs baseline: 1.0056x; 1.0056x over previous
;     __device__ bool next(int i, Unit& u) const {
;         const long L = (long)(pairs ? (i >> 1) : i) * G + c; u.alt = pairs ? (i & 1) : 0;
;         if (L >= (long)nwg + nsplit * nN) return false;
;         const bool tail = L >= nwg; const int j = tail ? (int)(L - nwg) : 0, ns = nsplit > 0 ? nsplit : 1;
;         int wgid = tail ? 0 : (int)L; { const int q = nwg / NXCD, r = nwg % NXCD, xcd = wgid % NXCD, off = wgid / NXCD; wgid = (xcd < r ? xcd * (q + 1) : r * (q + 1) + (xcd - r) * q) + off; }
; __device__ void tail_mix(const Params& p, LAS unsigned char* lds) {
;     ...
;     __syncthreads();
; }
.LBB0_242:
	v_mov_b32_e32 v0, v228
	s_cmpk_lt_i32 s50, 0x200
	s_waitcnt lgkmcnt(0)
	s_barrier
	s_mov_b32 s29, s50
	s_cselect_b64 s[40:41], -1, 0
	s_cmpk_gt_i32 s50, 0x1ff
	v_readfirstlane_b32 s4, v0
	s_cbranch_scc1 .LBB0_248
	s_ashr_i32 s22, s29, 31
	s_lshr_b32 s22, s22, 29
	s_mov_b32 s23, s29
	s_add_i32 s29, s29, s22
	s_and_b32 s22, s29, -8
	s_sub_i32 s30, s23, s22
	s_cmp_gt_i32 s30, -1
	s_mov_b64 s[42:43], -1
	s_cbranch_scc0 .LBB0_245
	s_lshl_b32 s33, s30, 6
	s_mov_b64 s[42:43], 0

;     __device__ bool next(int i, Unit& u) const {
;         const long L = (long)(pairs ? (i >> 1) : i) * G + c; u.alt = pairs ? (i & 1) : 0;
;         if (L >= (long)nwg + nsplit * nN) return false;
;         const bool tail = L >= nwg; const int j = tail ? (int)(L - nwg) : 0, ns = nsplit > 0 ? nsplit : 1;
;         int wgid = tail ? 0 : (int)L; { const int q = nwg / NXCD, r = nwg % NXCD, xcd = wgid % NXCD, off = wgid / NXCD; wgid = (xcd < r ? xcd * (q + 1) : r * (q + 1) + (xcd - r) * q) + off; }
; __device__ void tail_glu(const Params& p, int l, LAS unsigned char* lds) {
;     ...
;     __syncthreads();
; }
.LBB0_370:
	s_waitcnt lgkmcnt(0)
	v_mov_b32_e32 v16, v228
	s_barrier
	s_andn2_b64 vcc, exec, s[80:81]
	v_readfirstlane_b32 s29, v16
	s_cbranch_vccnz .LBB0_392
	s_ashr_i32 s52, s44, 31
	s_lshr_b32 s22, s52, 29
	s_add_i32 s33, s44, s22
	s_and_b32 s22, s33, -8
	s_sub_i32 s42, s44, s22
	s_mov_b64 s[58:59], s[16:17]
	s_mov_b64 s[50:51], s[6:7]
	s_cmp_gt_i32 s42, -1
	s_mov_b64 s[40:41], -1
	s_movk_i32 s16, 0x1100
	s_cbranch_scc0 .LBB0_373
	s_lshl_b32 s30, s42, 5
	s_mov_b64 s[40:41], 0
